# selected-branch softmax rescheduled to remove dependent back-to-back pairs: 16 fma, then 16 exp in place, then a depth-4 tree row-sum
# speedup vs baseline: 1.0250x; 1.0250x over previous
.LBB0_632:
	s_nop 9
	v_cndmask_b32_e64 v222, -v248, v203, s[6:7]
	v_fma_f32 v204, v66, s66, -v222
	v_fma_f32 v205, v67, s66, -v222
	v_fma_f32 v206, v68, s66, -v222
	v_fma_f32 v207, v69, s66, -v222
	v_fma_f32 v208, v70, s66, -v222
	v_fma_f32 v209, v71, s66, -v222
	v_fma_f32 v210, v72, s66, -v222
	v_fma_f32 v211, v73, s66, -v222
	v_fma_f32 v212, v74, s66, -v222
	v_fma_f32 v213, v75, s66, -v222
	v_fma_f32 v214, v76, s66, -v222
	v_fma_f32 v215, v77, s66, -v222
	v_fma_f32 v216, v78, s66, -v222
	v_fma_f32 v217, v79, s66, -v222
	v_fma_f32 v218, v80, s66, -v222
	v_fma_f32 v219, v81, s66, -v222
	v_exp_f32_e32 v204, v204
	v_exp_f32_e32 v205, v205
	v_exp_f32_e32 v206, v206
	v_exp_f32_e32 v207, v207
	v_exp_f32_e32 v208, v208
	v_exp_f32_e32 v209, v209
	v_exp_f32_e32 v210, v210
	v_exp_f32_e32 v211, v211
	v_exp_f32_e32 v212, v212
	v_exp_f32_e32 v213, v213
	v_exp_f32_e32 v214, v214
	v_exp_f32_e32 v215, v215
	v_exp_f32_e32 v216, v216
	v_exp_f32_e32 v217, v217
	v_exp_f32_e32 v218, v218
	v_exp_f32_e32 v219, v219
	v_add_f32_e32 v224, v204, v205
	v_add_f32_e32 v225, v206, v207
	v_add_f32_e32 v226, v208, v209
	v_add_f32_e32 v227, v210, v211
	v_add_f32_e32 v228, v212, v213
	v_add_f32_e32 v229, v214, v215
	v_add_f32_e32 v230, v216, v217
	v_add_f32_e32 v231, v218, v219
	v_add_f32_e32 v224, v224, v225
	v_add_f32_e32 v226, v226, v227
	v_add_f32_e32 v228, v228, v229
	v_add_f32_e32 v230, v230, v231
	v_add_f32_e32 v224, v224, v226
	v_add_f32_e32 v228, v228, v230
	v_add_f32_e32 v196, v224, v228
	v_cmp_lt_f32_e32 vcc, 0x43800000, v196
	s_cbranch_vccnz .Lsel_slow0

.LBB0_637:
	s_nop 6
	v_cndmask_b32_e64 v223, -v248, v185, s[4:5]
	v_fma_f32 v204, v66, s66, -v223
	v_fma_f32 v205, v67, s66, -v223
	v_fma_f32 v206, v68, s66, -v223
	v_fma_f32 v207, v69, s66, -v223
	v_fma_f32 v208, v70, s66, -v223
	v_fma_f32 v209, v71, s66, -v223
	v_fma_f32 v210, v72, s66, -v223
	v_fma_f32 v211, v73, s66, -v223
	v_fma_f32 v212, v74, s66, -v223
	v_fma_f32 v213, v75, s66, -v223
	v_fma_f32 v214, v76, s66, -v223
	v_fma_f32 v215, v77, s66, -v223
	v_fma_f32 v216, v78, s66, -v223
	v_fma_f32 v217, v79, s66, -v223
	v_fma_f32 v218, v80, s66, -v223
	v_fma_f32 v219, v81, s66, -v223
	v_exp_f32_e32 v204, v204
	v_exp_f32_e32 v205, v205
	v_exp_f32_e32 v206, v206
	v_exp_f32_e32 v207, v207
	v_exp_f32_e32 v208, v208
	v_exp_f32_e32 v209, v209
	v_exp_f32_e32 v210, v210
	v_exp_f32_e32 v211, v211
	v_exp_f32_e32 v212, v212
	v_exp_f32_e32 v213, v213
	v_exp_f32_e32 v214, v214
	v_exp_f32_e32 v215, v215
	v_exp_f32_e32 v216, v216
	v_exp_f32_e32 v217, v217
	v_exp_f32_e32 v218, v218
	v_exp_f32_e32 v219, v219
	v_add_f32_e32 v224, v204, v205
	v_add_f32_e32 v225, v206, v207
	v_add_f32_e32 v226, v208, v209
	v_add_f32_e32 v227, v210, v211
	v_add_f32_e32 v228, v212, v213
	v_add_f32_e32 v229, v214, v215
	v_add_f32_e32 v230, v216, v217
	v_add_f32_e32 v231, v218, v219
	v_add_f32_e32 v224, v224, v225
	v_add_f32_e32 v226, v226, v227
	v_add_f32_e32 v228, v228, v229
	v_add_f32_e32 v230, v230, v231
	v_add_f32_e32 v224, v224, v226
	v_add_f32_e32 v228, v228, v230
	v_add_f32_e32 v186, v224, v228
	v_cmp_lt_f32_e32 vcc, 0x43800000, v186
	s_cbranch_vccnz .Lsel_slow1
